# v8: v7 + mem-KV GEMM tiles remapped to CUs 128-159 (balances P1 at 13 rounds)
# speedup vs baseline: 1.0773x; 1.0033x over previous
;     __device__ bool next(int i, Unit& u) const {
;         const long L = (long)i * G + c; if (L >= nwg) return false;
;         int wgid = (int)L; { const int q = nwg / NXCD, r = nwg % NXCD, xcd = wgid % NXCD, off = wgid / NXCD; wgid = (xcd < r ? xcd * (q + 1) : r * (q + 1) + (xcd - r) * q) + off; }
;         const int nig = WGM * nN, gid = wgid / nig, fm = gid * WGM, gsz = (nM - fm) < WGM ? (nM - fm) : WGM;
;         u.pm = fm + ((wgid % nig) % gsz); u.pn = (wgid % nig) / gsz; return true;
;     }
; __global__ void __launch_bounds__(NTHREADS, 2) hymba_fwd(Args args) {
;     ...
;             pg8::EpiZ Em{MKV, 512, GT + l * 768 + 640, 0x1u, nullptr};
;             pg8::gemm_phase<pg8::EpiZ, false>(ldsl, XNM + (size_t)l * MMEM * DM, (const bf16_t*)(wl + WO_MEM), DM, MMEM / 256, 2, G, bx, wave, Em);
.LBB0_136:
	s_or_b64 exec, exec, s[2:3]
	s_mul_i32 s0, s81, s80
	s_and_b32 s81, s30, 0xffffffc0
	s_ashr_i32 s75, s97, 31
	s_cmpk_lt_i32 s97, 0xc80
	s_cselect_b64 s[2:3], -1, 0
	s_lshr_b32 s1, s75, 29
	v_writelane_b32 v254, s2, 3
	s_add_i32 s1, s97, s1
	s_ashr_i32 s93, s80, 31
	v_writelane_b32 v254, s3, 4
	s_ashr_i32 s3, s1, 3
	s_and_b32 s1, s1, -8
	s_sub_i32 s1, s97, s1
	s_add_i32 s4, s3, 16
	s_and_b32 s4, s4, 31
	s_lshl_b32 s4, s4, 3
	s_add_i32 s4, s4, s1
	s_cmp_eq_u32 s80, 0x100
	s_cselect_b32 s4, s4, s97
	s_cmp_lt_i32 s4, 32
	s_cselect_b64 s[4:5], -1, 0
	v_writelane_b32 v254, s4, 5
	s_lshl_b32 s2, s1, 2
	s_barrier
;     __device__ bool next(int i, Unit& u) const {
;         const long L = (long)i * G + c; if (L >= nwg) return false;
;         int wgid = (int)L; { const int q = nwg / NXCD, r = nwg % NXCD, xcd = wgid % NXCD, off = wgid / NXCD; wgid = (xcd < r ? xcd * (q + 1) : r * (q + 1) + (xcd - r) * q) + off; }
;         const int nig = WGM * nN, gid = wgid / nig, fm = gid * WGM, gsz = (nM - fm) < WGM ? (nM - fm) : WGM;
;         u.pm = fm + ((wgid % nig) % gsz); u.pn = (wgid % nig) / gsz; return true;
;     }
; __global__ void __launch_bounds__(NTHREADS, 2) hymba_fwd(Args args) {
;     ...
;             pg8::gemm_phase<pg8::EpiZ, false>(ldsl, XN, (const bf16_t*)(wl + WO_IN), DM, MT / 256, NZ / 256, G, bx, wave, E);
;             pg8::EpiZ Em{MKV, 512, GT + l * 768 + 640, 0x1u, nullptr};
;             pg8::gemm_phase<pg8::EpiZ, false>(ldsl, XNM + (size_t)l * MMEM * DM, (const bf16_t*)(wl + WO_MEM), DM, MMEM / 256, 2, G, bx, wave, Em);
	v_writelane_b32 v254, s5, 6
	s_sub_i32 s4, 0, s81
	s_cmp_lt_u32 s30, 64
	v_writelane_b32 v254, s4, 7
	s_cselect_b64 s[4:5], -1, 0
	v_writelane_b32 v254, s4, 8
	s_movk_i32 s83, 0xa1
	s_nop 0
	v_writelane_b32 v254, s5, 9
	s_movk_i32 s49, 0x191
	v_readlane_b32 s13, v254, 2
	s_cmpk_lt_i32 s13, 0xa00
	s_cselect_b64 s[4:5], -1, 0
	v_writelane_b32 v254, s4, 10
	s_cmpk_lt_i32 s13, 0x500
	s_mov_b32 s85, 0
	v_writelane_b32 v254, s5, 11
	s_cselect_b64 s[4:5], -1, 0
	v_writelane_b32 v254, s4, 12
	s_cmpk_lt_i32 s97, 0x500
	v_mov_b32_e32 v145, 0
	v_writelane_b32 v254, s5, 13
	s_cselect_b64 s[4:5], -1, 0
	v_writelane_b32 v254, s4, 14
	s_cmp_lt_i32 s1, 0
	s_movk_i32 s59, 0x4000
	v_writelane_b32 v254, s5, 15
	s_mul_i32 s4, s1, 5
	v_readlane_b32 s6, v254, 0
	v_readlane_b32 s7, v254, 1
	s_load_dword s5, s[6:7], 0xf8
	s_cselect_b32 s6, s49, 0x190
	s_cselect_b32 s7, s4, s2
	s_mov_b32 s60, 0x8000
	s_movk_i32 s50, 0x140
	s_waitcnt lgkmcnt(0)
	s_mul_i32 s55, s0, s5
	s_cselect_b32 s0, s83, 0xa0
	s_mul_i32 s0, s0, s1
	s_movk_i32 s5, 0x3b3
	s_cselect_b32 s5, s5, 0x3b2
	s_add_i32 s0, s0, s3
	s_ashr_i32 s2, s0, 31
	s_lshr_b32 s2, s2, 27
	s_add_i32 s2, s0, s2
	s_ashr_i32 s4, s2, 5
	s_and_b32 s2, s2, 0xffe0
	s_sub_i32 s2, s0, s2
	s_bfe_i32 s0, s2, 0x80000
	s_bfe_u32 s0, s0, 0x3000c
	s_add_i32 s8, s2, s0
	s_bfe_i32 s0, s8, 0x80000
	s_and_b32 s8, s8, 0xf8
	s_sub_i32 s2, s2, s8
	s_lshl_b32 s4, s4, 3
	s_sext_i32_i16 s9, s0
	s_sext_i32_i8 s2, s2
	s_lshr_b32 s0, s9, 3
	s_add_i32 s10, s4, s2
	s_ashr_i32 s2, s9, 3
	v_writelane_b32 v254, s2, 16
	s_cmpk_lt_i32 s97, 0x1d90
	s_mul_i32 s2, s5, s1
	s_cselect_b64 s[8:9], -1, 0
	s_add_i32 s2, s2, s3
	s_mul_hi_i32 s4, s2, 0x2e8ba2e9
	s_lshr_b32 s5, s4, 31
	s_ashr_i32 s4, s4, 5
	s_add_i32 s4, s4, s5
	s_mul_i32 s5, s4, 0xb0
	s_sub_i32 s5, s2, s5
	v_writelane_b32 v254, s8, 17
	s_bfe_u32 s2, s5, 0x3001c
	s_lshl_b32 s4, s4, 3
	v_writelane_b32 v254, s9, 18
	s_add_i32 s8, s5, s2
	s_sext_i32_i16 s9, s8
	s_and_b32 s8, s8, 0xfff8
	s_sub_i32 s5, s5, s8
	s_sext_i32_i16 s5, s5
	s_mul_i32 s1, s1, s6
	s_add_i32 s12, s4, s5
	s_ashr_i32 s4, s9, 3
	s_add_i32 s1, s1, s3
	v_writelane_b32 v254, s4, 19
	s_mul_hi_i32 s4, s1, 0x66666667
	s_lshr_b32 s5, s4, 31
	s_ashr_i32 s4, s4, 5
	s_add_i32 s4, s4, s5
	s_mul_i32 s5, s4, 0x50
	s_sub_i32 s1, s1, s5
	s_lshl_b32 s6, s4, 3
	s_bfe_i32 s4, s1, 0x80000
	s_bfe_u32 s4, s4, 0x3000c
	s_add_i32 s5, s1, s4
	s_bfe_i32 s4, s5, 0x80000
	s_and_b32 s5, s5, 0xf8
	s_sub_i32 s1, s1, s5
	s_sext_i32_i16 s8, s4
	s_sext_i32_i8 s1, s1
	s_add_i32 s14, s6, s1
	s_ashr_i32 s1, s8, 3
	v_writelane_b32 v254, s1, 20
	s_add_i32 s1, s3, 16
	s_and_b32 s1, s1, 31
	s_cmp_eq_u32 s80, 0x100
	s_cselect_b32 s1, s1, s3
	s_add_i32 s1, s7, s1
	s_ashr_i32 s3, s1, 31
	s_lshr_b32 s3, s3, 28
	s_add_i32 s3, s1, s3
	s_ashr_i32 s5, s3, 4
	s_and_b32 s3, s3, 0xfff0
	s_sub_i32 s1, s1, s3
	s_bfe_i32 s3, s1, 0x80000
	s_bfe_u32 s3, s3, 0x3000c
	s_add_i32 s3, s1, s3
	s_bfe_i32 s6, s3, 0x80000
	s_and_b32 s3, s3, 0xf8
	s_sub_i32 s1, s1, s3
	s_lshl_b32 s5, s5, 3
	s_sext_i32_i16 s7, s6
	s_sext_i32_i8 s1, s1
	s_add_i32 s16, s5, s1
	s_ashr_i32 s1, s7, 3
	s_lshr_b32 s4, s8, 3
	v_writelane_b32 v254, s1, 21
	s_mov_b32 s8, s10
	s_lshr_b32 s2, s9, 3
	s_ashr_i32 s11, s10, 31
	v_writelane_b32 v254, s8, 22
	s_bfe_i64 s[0:1], s[0:1], 0x100000
	s_lshl_b64 s[0:1], s[0:1], 19
	v_writelane_b32 v254, s9, 23
	s_lshl_b64 s[8:9], s[10:11], 19
	v_writelane_b32 v254, s8, 24
	s_lshr_b32 s6, s7, 3
	s_ashr_i32 s15, s14, 31
	v_writelane_b32 v254, s9, 25
	v_writelane_b32 v254, s0, 26
	s_ashr_i32 s17, s16, 31
	s_mov_b32 s61, 0xc000
	v_writelane_b32 v254, s1, 27
	s_add_i32 s0, s12, 0xfffffef0
	s_mul_hi_u32 s1, s0, 0x38e38e39
	s_lshr_b32 s1, s1, 1
	s_mul_i32 s3, s1, -9
	s_add_i32 s3, s3, s0
	s_lshl_b32 s0, s1, 11
	s_add_i32 s5, s0, 0x10000
	s_mul_hi_i32 s0, s12, 0x78787879
	s_lshr_b32 s1, s0, 31
	s_ashr_i32 s0, s0, 4
	s_add_i32 s0, s0, s1
	s_mul_i32 s1, s0, 0xffffffde
	s_add_i32 s7, s1, s12
	s_lshl_b32 s8, s0, 13
	s_bfe_i64 s[0:1], s[2:3], 0x100000
	s_lshl_b64 s[0:1], s[0:1], 19
	v_writelane_b32 v254, s0, 28
	v_mov_b32_e32 v173, 0x358637bd
	s_mov_b32 s62, 0x800000
	v_writelane_b32 v254, s1, 29
	s_mov_b32 s0, s14
	v_writelane_b32 v254, s0, 30
	s_movk_i32 s63, 0x1400
	v_mov_b32_e32 v175, 0x1000
	v_writelane_b32 v254, s1, 31
	s_lshl_b64 s[0:1], s[14:15], 19
	v_writelane_b32 v254, s0, 32
	v_mov_b32_e32 v177, 0x2000
	v_mov_b32_e32 v184, 1
	v_writelane_b32 v254, s1, 33
	s_bfe_i64 s[0:1], s[4:5], 0x100000
	s_lshl_b64 s[0:1], s[0:1], 19
	v_writelane_b32 v254, s0, 34
	s_mov_b32 s51, 0x663d81
	s_movk_i32 s52, 0xfd7f
	v_writelane_b32 v254, s1, 35
	s_mov_b32 s0, s16
	v_writelane_b32 v254, s0, 36
	v_mov_b64_e32 v[146:147], 0x500
	v_mov_b64_e32 v[148:149], 0x4ff
	v_writelane_b32 v254, s1, 37
	s_lshl_b64 s[0:1], s[16:17], 19
	v_writelane_b32 v254, s0, 38
	v_mov_b64_e32 v[150:151], 0x1d8f
	s_movk_i32 s53, 0x5a
	v_writelane_b32 v254, s1, 39
	s_bfe_i64 s[0:1], s[6:7], 0x100000
	s_lshl_b64 s[0:1], s[0:1], 19
	v_writelane_b32 v254, s0, 40
	s_cmpk_lt_i32 s12, 0x110
	s_movk_i32 s54, 0xa10
	v_writelane_b32 v254, s1, 41
	s_cselect_b32 s1, s7, s3
	s_cselect_b32 s0, s8, s5
	s_mulk_i32 s1, 0xf8
	s_ashr_i32 s2, s0, 31
	s_ashr_i32 s3, s1, 31
	s_add_u32 s0, s0, s1
	s_addc_u32 s1, s2, s3
	s_lshl_b64 s[0:1], s[0:1], 11
	v_writelane_b32 v254, s12, 42
	s_add_u32 s0, s0, 0xfffff800
	v_writelane_b32 v254, s0, 43
	s_addc_u32 s0, s1, -1
	s_bitcmp1_b32 s13, 0
	v_writelane_b32 v254, s0, 44
	s_cselect_b64 s[0:1], -1, 0
	v_writelane_b32 v254, s0, 45
	s_bitcmp1_b32 s80, 0
	s_cselect_b64 s[56:57], -1, 0
	v_writelane_b32 v254, s1, 46
	s_lshl_b32 s0, s13, 7
	v_writelane_b32 v254, s0, 47
	s_add_i32 s0, 0, 0x20200
	v_writelane_b32 v254, s0, 48
	s_add_i32 s0, 0, 0x20204
	v_writelane_b32 v254, s0, 49
	s_add_i32 s0, 0, 0x1c008
	v_writelane_b32 v254, s0, 50
	s_add_i32 s0, 0, 0x1c010
	v_writelane_b32 v254, s0, 51
	s_add_i32 s0, 0, 0x15100
	v_writelane_b32 v254, s0, 52
	s_mov_b64 s[0:1], -1
	v_writelane_b32 v254, s0, 53
	s_add_i32 s64, 0, 0x11000
	s_lshl_b32 s58, s80, 7
	v_writelane_b32 v254, s1, 54
	s_mov_b64 s[0:1], 0
	v_writelane_b32 v254, s0, 55
	v_writelane_b32 v255, s80, 0
	s_mov_b32 s74, 0x28000
	v_writelane_b32 v254, s1, 56
	v_writelane_b32 v254, s64, 57
	v_writelane_b32 v254, s97, 58
	v_writelane_b32 v254, s93, 59
	v_writelane_b32 v254, s75, 60
	v_writelane_b32 v254, s58, 61
	v_writelane_b32 v255, s81, 1
	v_writelane_b32 v254, s56, 62
	v_writelane_b32 v255, s81, 2
	s_mov_b32 s65, 0x50000
	s_mov_b32 s66, 0x78000
	s_movk_i32 s67, 0x1000
	s_movk_i32 s68, 0x5000
	s_mov_b32 s69, 0x9000
	s_mov_b32 s72, 0xd000
	s_movk_i32 s73, 0x1600
	s_mov_b64 s[94:95], 0x80
	s_mov_b32 s82, 0x3a800000
	s_mov_b32 s36, 0x3fb8aa3b
	s_mov_b64 s[70:71], 0x28000
	s_mov_b32 s78, 0x358637bd
	s_mov_b32 s76, 0xbfb8aa3b
	s_mov_b32 s2, s85
	v_writelane_b32 v254, s57, 63
	v_writelane_b32 v255, s55, 3
	s_branch .LBB0_140
